# mla_finalize item loop: static s_setprio 1 for waves 4-7, reset at phase exit; on top of the conv and GEMM raises
# baseline (speedup 1.0000x reference)
; DI void mla_finalize(PPtr p, int j, ldsp lds, int tid, int wave, int lane) {
;     const bf16_t* aout = (const bf16_t*)(p->ws + WS_AOUT); const bf16_t* qraw = (const bf16_t*)(p->ws + WS_QRAW); const bf16_t* kvraw = (const bf16_t*)(p->ws + WS_KVRAW);
;     bf16_t* Qb = (bf16_t*)(p->ws + WS_QB); bf16_t* Kb = (bf16_t*)(p->ws + WS_KB); bf16_t* Vt = (bf16_t*)(p->ws + WS_VT);
;     const float* qg = p->mla_q_gain + j * QKH; const float* kg = p->mla_k_gain + j * QKH;
;     constexpr int VTP = 40;
;     const int head = lane >> 2, sub = lane & 3;
;     for (int item = blockIdx.x; item < T / 32; item += gridDim.x) {
;         const int t0 = item * 32, b = t0 >> 12, s0 = t0 & 4095;
;         for (int rr = 0; rr < 4; ++rr) {
;             const int tok = wave * 4 + rr, t = t0 + tok;
;             float ssq = 0.f, sskv = 0.f;
;             if (lane < 48) { const u32x4 w = *(const u32x4*)(aout + (size_t)t * ADIMP + 8 * lane);
; #pragma unroll
;                 for (int i = 0; i < 4; ++i) { const float a = bflo(w[i]), c = bfhi(w[i]); ssq += a * a + c * c; } }
;             if (lane < 32) { const u32x4 w = *(const u32x4*)(aout + (size_t)t * ADIMP + QL + 8 * lane);
; #pragma unroll
;                 for (int i = 0; i < 4; ++i) { const float a = bflo(w[i]), c = bfhi(w[i]); sskv += a * a + c * c; } }
;             const float rq = rsqrtf(wave_sum(ssq) * (1.0f / QL) + EPS), rkv = rsqrtf(wave_sum(sskv) * (1.0f / KVL) + EPS);
;             float cs, sn;
;             { const int fi = lane & 15; const float inv = exp2f(-(float)fi * (13.287712379549449f / 16.0f));
;               const float ang = (float)p->pos[t] * inv; double rev = (double)ang * 0.15915494309189535; rev -= floor(rev); const float rv = (float)rev;
;               cs = __builtin_amdgcn_cosf(rv); sn = __builtin_amdgcn_sinf(rv); }
;             float cj[8], sj[8];
; #pragma unroll
;             for (int i = 0; i < 8; ++i) { cj[i] = __shfl(cs, 8 * (sub & 1) + i); sj[i] = __shfl(sn, 8 * (sub & 1) + i); }
;     ...
;             { const bf16_t* src = kvraw + (size_t)t * 2048 + head * 128 + 64 + 16 * sub;
; #pragma unroll
;               for (int g = 0; g < 2; ++g) { const u32x4 w = *(const u32x4*)(src + 8 * g);
; #pragma unroll
;                   for (int i = 0; i < 4; ++i) { const int d = head * 64 + 16 * sub + 8 * g + 2 * i;
;                       *(LAS bf16_t*)(lds + ((d) * VTP + tok) * 2) = f2bf(bflo(w[i]) * rkv);
.LBB0_781:
	s_movk_i32 s7, 0x800
	s_and_b64 vcc, exec, s[4:5]
	v_readlane_b32 s51, v254, 40
	s_cbranch_vccz .LBB0_923
	v_readlane_b32 s2, v254, 18
	v_readlane_b32 s3, v254, 19
	v_mov_b32_e32 v2, v153
	s_andn2_b64 vcc, exec, s[2:3]
	v_cndmask_b32_e64 v0, 0, 1, s[2:3]
	v_cmp_ne_u32_e64 s[0:1], 1, v0
	v_readfirstlane_b32 s4, v2
	s_cbranch_vccnz .LBB0_791
	s_nop 3
	s_lshr_b32 s32, s4, 6
	s_cmp_ge_u32 s32, 4
	s_cbranch_scc0 .Lfin_prio_skip
	s_setprio 1
.Lfin_prio_skip:
	v_xor_b32_e32 v0, 1, v204
	v_cmp_lt_i32_e64 s[6:7], v0, v214
	v_readlane_b32 s12, v255, 3
	v_readlane_b32 s13, v255, 4
	v_cndmask_b32_e64 v0, v204, v0, s[6:7]
	v_lshlrev_b32_e32 v39, 2, v0
	v_xor_b32_e32 v0, 2, v204
	v_cmp_lt_i32_e64 s[6:7], v0, v214
	s_load_dwordx2 s[2:3], s[12:13], 0xc8
	v_bfe_u32 v38, v2, 2, 4
	v_cndmask_b32_e64 v0, v204, v0, s[6:7]
	v_lshlrev_b32_e32 v77, 2, v0
	v_xor_b32_e32 v0, 4, v204
	v_cmp_lt_i32_e64 s[6:7], v0, v214
	v_lshlrev_b32_e32 v10, 3, v2
	s_waitcnt lgkmcnt(0)
	s_add_u32 s14, s2, 0xd240000
	v_cndmask_b32_e64 v0, v204, v0, s[6:7]
	s_waitcnt vmcnt(2)
	v_lshlrev_b32_e32 v130, 2, v0
	v_xor_b32_e32 v0, 8, v204
	v_cmp_lt_i32_e64 s[6:7], v0, v214
	s_addc_u32 s15, s3, 0
	s_mov_b64 s[18:19], 0x11a40000
	v_cndmask_b32_e64 v0, v204, v0, s[6:7]
	v_lshlrev_b32_e32 v131, 2, v0
	v_xor_b32_e32 v0, 16, v204
	v_cmp_lt_i32_e64 s[6:7], v0, v214
	s_add_u32 s16, s2, 0x1ba40000
	v_and_b32_e32 v3, 63, v2
	v_cndmask_b32_e64 v0, v204, v0, s[6:7]
	v_lshlrev_b32_e32 v132, 2, v0
	v_and_b32_e32 v0, 15, v2
	v_cvt_f32_ubyte0_e32 v0, v0
	v_mul_f32_e32 v4, 0xbf549a78, v0
	s_mov_b32 s6, 0xc2fc0000
	v_cmp_gt_f32_e64 s[6:7], s6, v4
	v_mov_b32_e32 v4, 0x42800000
	s_addc_u32 s17, s3, 0
	v_cndmask_b32_e64 v4, 0, v4, s[6:7]
	v_fmac_f32_e32 v4, 0xbf549a78, v0
	v_exp_f32_e32 v0, v4
	v_xor_b32_e32 v4, 32, v204
	v_cmp_lt_i32_e64 s[8:9], v4, v214
	s_ashr_i32 s20, s4, 4
	s_and_b32 s21, s20, -4
	v_cndmask_b32_e64 v4, v204, v4, s[8:9]
	v_lshlrev_b32_e32 v133, 2, v4
	v_not_b32_e32 v4, 63
	v_cndmask_b32_e64 v4, 0, v4, s[6:7]
	v_ldexp_f32 v134, v0, v4
	v_and_b32_e32 v0, 64, v204
	v_and_or_b32 v11, v10, 8, v0
	v_lshlrev_b32_e32 v0, 8, v38
	s_load_dwordx4 s[8:11], s[12:13], 0x68
	s_nop 0
	s_load_dwordx2 s[12:13], s[12:13], 0x10
	v_lshl_add_u64 v[6:7], s[2:3], 0, v[0:1]
	v_lshl_add_u64 v[40:41], v[6:7], 0, s[18:19]
	v_mul_u32_u24_e32 v0, 0x60, v38
	v_readlane_b32 s18, v254, 57
	v_lshlrev_b32_e32 v0, 1, v0
	v_readlane_b32 s19, v254, 58
	v_lshl_add_u64 v[6:7], s[2:3], 0, v[0:1]
	v_lshlrev_b32_e32 v0, 4, v3
	v_ashrrev_i32_e32 v12, 2, v2
	s_lshl_b64 s[18:19], s[18:19], 2
	v_and_b32_e32 v5, 3, v2
	v_lshl_add_u64 v[42:43], s[14:15], 0, v[0:1]
	v_and_b32_e32 v10, 24, v10
	v_mul_lo_u32 v0, v12, 40
	s_waitcnt lgkmcnt(0)
	s_add_u32 s8, s8, s18
	v_add_lshl_u32 v15, v0, v10, 1
	s_addc_u32 s9, s9, s19
	v_lshlrev_b32_e32 v0, 5, v5
	v_lshlrev_b32_e32 v8, 4, v5
	v_lshl_add_u64 v[44:45], s[8:9], 0, v[0:1]
	s_add_u32 s8, s10, s18
	v_lshl_or_b32 v13, v38, 6, v8
	s_addc_u32 s9, s11, s19
	v_cmp_gt_u32_e32 vcc, 48, v3
	v_cmp_gt_u32_e64 s[4:5], 32, v3
	v_lshl_add_u64 v[46:47], s[8:9], 0, v[0:1]
	v_mul_u32_u24_e32 v0, 40, v13
	v_ashrrev_i32_e32 v13, 31, v12
	v_add_u32_e32 v3, 0x200, v2
	v_lshlrev_b64 v[48:49], 13, v[12:13]
	v_ashrrev_i32_e32 v12, 2, v3
	v_mul_lo_u32 v3, v12, 40
	v_lshlrev_b32_e32 v4, 3, v5
	v_cmp_gt_u32_e64 s[6:7], 2, v5
	v_add_lshl_u32 v5, v3, v10, 1
	v_ashrrev_i32_e32 v13, 31, v12
	v_add_u32_e32 v3, 0x400, v2
	v_lshlrev_b64 v[50:51], 13, v[12:13]
	v_ashrrev_i32_e32 v12, 2, v3
	v_mul_lo_u32 v3, v12, 40
	v_lshlrev_b32_e32 v135, 2, v11
	v_add_lshl_u32 v11, v3, v10, 1
	v_ashrrev_i32_e32 v13, 31, v12
	v_add_u32_e32 v3, 0x600, v2
	v_lshlrev_b64 v[52:53], 13, v[12:13]
	v_ashrrev_i32_e32 v12, 2, v3
	v_mul_lo_u32 v3, v12, 40
	v_add_lshl_u32 v17, v3, v10, 1
	v_ashrrev_i32_e32 v13, 31, v12
	v_add_u32_e32 v3, 0x800, v2
	v_lshlrev_b64 v[54:55], 13, v[12:13]
	v_ashrrev_i32_e32 v12, 2, v3
	v_mul_lo_u32 v3, v12, 40
	v_add_lshl_u32 v18, v3, v10, 1
	v_ashrrev_i32_e32 v13, 31, v12
	v_add_u32_e32 v3, 0xa00, v2
	v_lshlrev_b64 v[56:57], 13, v[12:13]
	v_ashrrev_i32_e32 v12, 2, v3
	v_mul_lo_u32 v3, v12, 40
	v_add_lshl_u32 v19, v3, v10, 1
	v_ashrrev_i32_e32 v13, 31, v12
	v_add_u32_e32 v3, 0xc00, v2
	v_lshlrev_b64 v[58:59], 13, v[12:13]
	v_ashrrev_i32_e32 v12, 2, v3
	v_add_u32_e32 v2, 0xe00, v2
	v_mul_lo_u32 v3, v12, 40
	v_ashrrev_i32_e32 v2, 2, v2
	v_add_lshl_u32 v20, v3, v10, 1
	v_ashrrev_i32_e32 v13, 31, v12
	v_mul_lo_u32 v3, v2, 40
	v_mov_b32_e32 v9, v1
	v_lshlrev_b64 v[60:61], 13, v[12:13]
	v_add_lshl_u32 v12, v3, v10, 1
	v_ashrrev_i32_e32 v3, 31, v2
	v_lshlrev_b64 v[62:63], 13, v[2:3]
	v_lshl_add_u64 v[2:3], v[6:7], 0, v[8:9]
	s_mov_b64 s[8:9], 0xea40000
	v_lshl_add_u64 v[66:67], v[2:3], 0, s[8:9]
	s_lshl_b32 s8, s20, 1
	s_and_b32 s8, s8, -8
	s_add_i32 s8, s8, 0
	v_or_b32_e32 v14, 32, v4
	v_or_b32_e32 v16, 64, v4
	v_and_b32_e32 v230, 63, v153
	v_mul_u32_u24_e32 v230, 0x50, v230
	v_add_u32_e32 v143, s8, v230
	v_lshrrev_b32_e32 v230, 2, v153
	v_and_b32_e32 v231, 63, v230
	v_lshrrev_b32_e32 v230, 6, v230
	v_lshl_or_b32 v230, v231, 4, v230
	v_lshlrev_b32_e32 v48, 13, v230
	v_mov_b32_e32 v49, v1
	v_add_u32_e32 v50, 0x4000, v48
	v_mov_b32_e32 v51, v1
	v_add_u32_e32 v52, 0x8000, v48
	v_mov_b32_e32 v53, v1
	v_add_u32_e32 v54, 0xc000, v48
	v_mov_b32_e32 v55, v1
	v_add_u32_e32 v56, 0x10000, v48
	v_mov_b32_e32 v57, v1
	v_add_u32_e32 v58, 0x14000, v48
	v_mov_b32_e32 v59, v1
	v_add_u32_e32 v60, 0x18000, v48
	v_mov_b32_e32 v61, v1
	v_add_u32_e32 v62, 0x1c000, v48
	v_mov_b32_e32 v63, v1
	v_readlane_b32 s8, v254, 2
	v_or_b32_e32 v136, 4, v135
	v_or_b32_e32 v137, 8, v135
	v_or_b32_e32 v138, 12, v135
	v_or_b32_e32 v139, 16, v135
	v_or_b32_e32 v140, 20, v135
	v_or_b32_e32 v141, 24, v135
	v_or_b32_e32 v142, 28, v135
	v_lshl_add_u64 v[64:65], s[14:15], 0, v[8:9]
	s_add_i32 s18, s8, s21
	v_lshlrev_b32_e32 v0, 1, v4
	v_lshlrev_b32_e32 v68, 1, v14
	v_lshlrev_b32_e32 v70, 1, v16
	v_lshlrev_b32_e32 v72, 1, v8
	v_lshlrev_b32_e32 v74, 1, v10
	v_add_u32_e32 v144, 0, v15
	v_add_u32_e32 v145, 0, v5
	v_add_u32_e32 v146, 0, v11
	v_add_u32_e32 v147, 0, v17
	v_add_u32_e32 v148, 0, v18
	v_add_u32_e32 v149, 0, v19
	v_add_u32_e32 v150, 0, v20
	v_add_u32_e32 v151, 0, v12
	s_mov_b32 s19, s64
	s_branch .LBB0_785

; #define LAS __attribute__((address_space(3)))
; DI unsigned xb_xcc_id() { return (unsigned)__builtin_amdgcn_s_getreg((3 << 11) | 20) & 0xFu; }
; DI void xcd_barrier(unsigned* bar_, volatile LAS unsigned* st_) {
;     XcdBarrier b; b.bar = bar_; b.st = st_; b.x = 0;
;     asm volatile("s_waitcnt vmcnt(0)" ::: "memory");
;     __syncthreads();
;     if (threadIdx.x == 0) {
;         unsigned* bar = b.bar; b.x = xb_xcc_id();
;         __builtin_amdgcn_s_waitcnt(0);
;         unsigned nloc = b.st[0], nx = b.st[1];
;         if (nloc == 0u) { xcd_barrier_complete(bar, b.x, nloc, nx); b.st[0] = nloc; b.st[1] = nx; }
.LBB0_791:
	s_setprio 0
	v_readlane_b32 s2, v255, 3
	v_readlane_b32 s3, v255, 4
	s_waitcnt vmcnt(0)
	s_nop 0
	v_writelane_b32 v255, s2, 3
	s_barrier
	s_nop 0
	v_writelane_b32 v255, s3, 4
	s_and_saveexec_b64 s[2:3], s[66:67]
	s_cbranch_execz .LBB0_843
	v_readlane_b32 s4, v255, 3
	v_readlane_b32 s7, v254, 28
	v_readlane_b32 s5, v255, 4
	s_load_dwordx2 s[4:5], s[4:5], 0xc8
	v_mov_b32_e32 v0, s7
	s_getreg_b32 s6, hwreg(HW_REG_XCC_ID, 0, 4)
	s_waitcnt vmcnt(0) expcnt(0) lgkmcnt(0)
	ds_read_b32 v3, v0
	v_readlane_b32 s7, v254, 29
	s_and_b32 s20, s6, 15
	s_waitcnt lgkmcnt(0)
	v_cmp_ne_u32_e32 vcc, 0, v3
	v_mov_b32_e32 v0, s7
	ds_read_b32 v2, v0
	s_cbranch_vccnz .LBB0_807
	s_add_u32 s6, s4, 0x1000
	s_addc_u32 s7, s5, 0
	s_add_u32 s8, s4, 0x1100
	s_addc_u32 s9, s5, 0
	s_add_u32 s10, s4, 0x1200
	s_addc_u32 s11, s5, 0
	s_add_u32 s12, s4, 0x1300
	s_addc_u32 s13, s5, 0
	s_mov_b32 s21, 1
	s_branch .LBB0_795
